# MLA softmax exp/sum/pack block rewritten with packed f32 adds (82 VALU instead of 112)
# baseline (speedup 1.0000x reference)
.LBB0_994:
	v_mov_b32_e32 v198, v214
	v_mov_b32_e32 v199, v214
	v_pk_add_f32 v[82:83], v[82:83], v[198:199] neg_lo:[0,1] neg_hi:[0,1]
	v_pk_add_f32 v[84:85], v[84:85], v[198:199] neg_lo:[0,1] neg_hi:[0,1]
	v_pk_add_f32 v[86:87], v[86:87], v[198:199] neg_lo:[0,1] neg_hi:[0,1]
	v_pk_add_f32 v[88:89], v[88:89], v[198:199] neg_lo:[0,1] neg_hi:[0,1]
	v_pk_add_f32 v[90:91], v[90:91], v[198:199] neg_lo:[0,1] neg_hi:[0,1]
	v_pk_add_f32 v[92:93], v[92:93], v[198:199] neg_lo:[0,1] neg_hi:[0,1]
	v_pk_add_f32 v[94:95], v[94:95], v[198:199] neg_lo:[0,1] neg_hi:[0,1]
	v_pk_add_f32 v[96:97], v[96:97], v[198:199] neg_lo:[0,1] neg_hi:[0,1]
	v_pk_add_f32 v[66:67], v[66:67], v[198:199] neg_lo:[0,1] neg_hi:[0,1]
	v_pk_add_f32 v[68:69], v[68:69], v[198:199] neg_lo:[0,1] neg_hi:[0,1]
	v_pk_add_f32 v[70:71], v[70:71], v[198:199] neg_lo:[0,1] neg_hi:[0,1]
	v_pk_add_f32 v[72:73], v[72:73], v[198:199] neg_lo:[0,1] neg_hi:[0,1]
	v_pk_add_f32 v[74:75], v[74:75], v[198:199] neg_lo:[0,1] neg_hi:[0,1]
	v_pk_add_f32 v[76:77], v[76:77], v[198:199] neg_lo:[0,1] neg_hi:[0,1]
	v_pk_add_f32 v[78:79], v[78:79], v[198:199] neg_lo:[0,1] neg_hi:[0,1]
	v_pk_add_f32 v[80:81], v[80:81], v[198:199] neg_lo:[0,1] neg_hi:[0,1]
	v_exp_f32_e32 v82, v82
	v_exp_f32_e32 v83, v83
	v_exp_f32_e32 v84, v84
	v_exp_f32_e32 v85, v85
	v_exp_f32_e32 v86, v86
	v_exp_f32_e32 v87, v87
	v_exp_f32_e32 v88, v88
	v_exp_f32_e32 v89, v89
	v_exp_f32_e32 v90, v90
	v_exp_f32_e32 v91, v91
	v_exp_f32_e32 v92, v92
	v_exp_f32_e32 v93, v93
	v_exp_f32_e32 v94, v94
	v_exp_f32_e32 v95, v95
	v_exp_f32_e32 v96, v96
	v_exp_f32_e32 v97, v97
	v_exp_f32_e32 v66, v66
	v_exp_f32_e32 v67, v67
	v_exp_f32_e32 v68, v68
	v_exp_f32_e32 v69, v69
	v_exp_f32_e32 v70, v70
	v_exp_f32_e32 v71, v71
	v_exp_f32_e32 v72, v72
	v_exp_f32_e32 v73, v73
	v_exp_f32_e32 v74, v74
	v_exp_f32_e32 v75, v75
	v_exp_f32_e32 v76, v76
	v_exp_f32_e32 v77, v77
	v_exp_f32_e32 v78, v78
	v_exp_f32_e32 v79, v79
	v_exp_f32_e32 v80, v80
	v_exp_f32_e32 v81, v81
	v_pk_add_f32 v[194:195], v[82:83], v[84:85]
	v_pk_add_f32 v[196:197], v[86:87], v[88:89]
	v_pk_add_f32 v[200:201], v[90:91], v[92:93]
	v_pk_add_f32 v[198:199], v[94:95], v[96:97]
	v_pk_add_f32 v[194:195], v[194:195], v[196:197]
	v_pk_add_f32 v[200:201], v[200:201], v[198:199]
	v_pk_add_f32 v[194:195], v[194:195], v[200:201]
	v_pk_add_f32 v[196:197], v[66:67], v[68:69]
	v_pk_add_f32 v[198:199], v[70:71], v[72:73]
	v_pk_add_f32 v[196:197], v[196:197], v[198:199]
	v_pk_add_f32 v[198:199], v[74:75], v[76:77]
	v_pk_add_f32 v[200:201], v[78:79], v[80:81]
	v_pk_add_f32 v[198:199], v[198:199], v[200:201]
	v_pk_add_f32 v[196:197], v[196:197], v[198:199]
	v_pk_add_f32 v[194:195], v[194:195], v[196:197]
	s_nop 0
	v_add_f32_e32 v194, v194, v195
	v_cvt_pk_bf16_f32 v82, v82, v83
	v_cvt_pk_bf16_f32 v83, v84, v85
	v_cvt_pk_bf16_f32 v84, v86, v87
	v_cvt_pk_bf16_f32 v85, v88, v89
	v_cvt_pk_bf16_f32 v86, v90, v91
	v_cvt_pk_bf16_f32 v87, v92, v93
	v_cvt_pk_bf16_f32 v88, v94, v95
	v_cvt_pk_bf16_f32 v89, v96, v97
	v_cvt_pk_bf16_f32 v66, v66, v67
	v_cvt_pk_bf16_f32 v67, v68, v69
	v_cvt_pk_bf16_f32 v68, v70, v71
	v_cvt_pk_bf16_f32 v69, v72, v73
	v_cvt_pk_bf16_f32 v70, v74, v75
	v_cvt_pk_bf16_f32 v71, v76, v77
	v_cvt_pk_bf16_f32 v72, v78, v79
	v_cvt_pk_bf16_f32 v73, v80, v81
	ds_read_b128 v[74:77], v215 offset:25632
	ds_read_b128 v[78:81], v215 offset:30240
	ds_read_b128 v[90:93], v215 offset:34848
	ds_read_b128 v[94:97], v215 offset:39456
	s_waitcnt lgkmcnt(7)
	v_mfma_f32_32x32x16_bf16 v[50:65], v[82:85], v[178:181], v[50:65]
	s_waitcnt lgkmcnt(6)
	v_mfma_f32_32x32x16_bf16 v[34:49], v[82:85], v[174:177], v[34:49]
	s_waitcnt lgkmcnt(5)
	v_mfma_f32_32x32x16_bf16 v[18:33], v[82:85], v[166:169], v[18:33]
	s_waitcnt lgkmcnt(4)
	v_mfma_f32_32x32x16_bf16 v[2:17], v[82:85], v[170:173], v[2:17]
	ds_read_b128 v[82:85], v215 offset:25664
	ds_read_b128 v[166:169], v215 offset:30272
	ds_read_b128 v[170:173], v215 offset:34880
	ds_read_b128 v[174:177], v215 offset:39488
	s_waitcnt lgkmcnt(7)
	v_mfma_f32_32x32x16_bf16 v[50:65], v[86:89], v[74:77], v[50:65]
	s_waitcnt lgkmcnt(6)
	v_mfma_f32_32x32x16_bf16 v[34:49], v[86:89], v[78:81], v[34:49]
	s_waitcnt lgkmcnt(5)
	v_mfma_f32_32x32x16_bf16 v[18:33], v[86:89], v[90:93], v[18:33]
	s_waitcnt lgkmcnt(4)
	v_mfma_f32_32x32x16_bf16 v[2:17], v[86:89], v[94:97], v[2:17]
	ds_read_b128 v[74:77], v215 offset:25696
	ds_read_b128 v[78:81], v215 offset:30304
	ds_read_b128 v[86:89], v215 offset:34912
	ds_read_b128 v[90:93], v215 offset:39520
	s_waitcnt lgkmcnt(7)
	v_mfma_f32_32x32x16_bf16 v[50:65], v[66:69], v[82:85], v[50:65]
	s_waitcnt lgkmcnt(6)
	v_mfma_f32_32x32x16_bf16 v[34:49], v[66:69], v[166:169], v[34:49]
	s_waitcnt lgkmcnt(5)
	v_mfma_f32_32x32x16_bf16 v[18:33], v[66:69], v[170:173], v[18:33]
	s_waitcnt lgkmcnt(4)
	v_mfma_f32_32x32x16_bf16 v[2:17], v[66:69], v[174:177], v[2:17]
	s_waitcnt lgkmcnt(3)
	v_mfma_f32_32x32x16_bf16 v[50:65], v[70:73], v[74:77], v[50:65]
	s_bitcmp1_b32 s30, 0
	s_cselect_b32 s16, 0xac00, 0
	s_add_i32 s16, s16, 0
	v_add_u32_e32 v66, s16, v193
	s_waitcnt vmcnt(4)
	ds_write_b128 v66, v[146:149]
	s_waitcnt vmcnt(3)
	ds_write_b128 v66, v[154:157] offset:12800
	v_add_u32_e32 v66, s16, v203
	s_add_i32 s26, s26, 64
	s_waitcnt lgkmcnt(4)
	v_mfma_f32_32x32x16_bf16 v[34:49], v[70:73], v[78:81], v[34:49]
	v_add_f32_e32 v192, v192, v194
	s_waitcnt vmcnt(2)
	ds_write_b128 v66, v[158:161] offset:256
	v_add_u32_e32 v66, s16, v204
	v_lshl_add_u64 v[186:187], v[186:187], 0, s[76:77]
	s_cmp_eq_u32 s27, s30
	s_waitcnt vmcnt(1)
	ds_write_b128 v66, v[150:153] offset:25600
	s_waitcnt vmcnt(0)
	ds_write_b128 v66, v[162:165] offset:34816
	s_waitcnt lgkmcnt(0)
	v_mfma_f32_32x32x16_bf16 v[18:33], v[70:73], v[86:89], v[18:33]
	s_barrier
	v_mfma_f32_32x32x16_bf16 v[2:17], v[70:73], v[90:93], v[2:17]
	s_cbranch_scc0 .LBB0_987
	v_add_u32_e32 v0, s16, v202
	ds_read_b128 v[66:69], v0
	ds_read_b128 v[70:73], v0 offset:32
	ds_read_b128 v[74:77], v0 offset:64
	ds_read_b128 v[78:81], v0 offset:96
	ds_read_b128 v[146:149], v0 offset:128
	ds_read_b128 v[150:153], v0 offset:160
	ds_read_b128 v[154:157], v0 offset:192
	ds_read_b128 v[158:161], v0 offset:224
	s_waitcnt lgkmcnt(7)
	v_mfma_f32_32x32x16_bf16 v[82:97], v[66:69], v[142:145], 0
	s_waitcnt lgkmcnt(6)
	v_mfma_f32_32x32x16_bf16 v[82:97], v[70:73], v[138:141], v[82:97]
	s_waitcnt lgkmcnt(5)
	v_mfma_f32_32x32x16_bf16 v[82:97], v[74:77], v[134:137], v[82:97]
	s_waitcnt lgkmcnt(4)
	v_mfma_f32_32x32x16_bf16 v[82:97], v[78:81], v[130:133], v[82:97]
	ds_read_b128 v[66:69], v0 offset:256
	ds_read_b128 v[70:73], v0 offset:288
	ds_read_b128 v[74:77], v0 offset:320
	ds_read_b128 v[78:81], v0 offset:352
	s_waitcnt lgkmcnt(7)
	v_mfma_f32_32x32x16_bf16 v[82:97], v[146:149], v[126:129], v[82:97]
	s_waitcnt lgkmcnt(6)
	v_mfma_f32_32x32x16_bf16 v[82:97], v[150:153], v[122:125], v[82:97]
	s_waitcnt lgkmcnt(5)
	v_mfma_f32_32x32x16_bf16 v[82:97], v[154:157], v[118:121], v[82:97]
	s_waitcnt lgkmcnt(4)
	v_mfma_f32_32x32x16_bf16 v[82:97], v[158:161], v[114:117], v[82:97]
	ds_read_b128 v[146:149], v0 offset:12800
	ds_read_b128 v[150:153], v0 offset:12832
	ds_read_b128 v[154:157], v0 offset:12864
	ds_read_b128 v[158:161], v0 offset:12896
	s_waitcnt lgkmcnt(7)
	v_mfma_f32_32x32x16_bf16 v[82:97], v[66:69], v[110:113], v[82:97]
	ds_read_b128 v[162:165], v0 offset:12928
	ds_read_b128 v[166:169], v0 offset:12960
	ds_read_b128 v[170:173], v0 offset:12992
	ds_read_b128 v[174:177], v0 offset:13024
	s_waitcnt lgkmcnt(10)
	v_mfma_f32_32x32x16_bf16 v[82:97], v[70:73], v[106:109], v[82:97]
	s_waitcnt lgkmcnt(9)
	v_mfma_f32_32x32x16_bf16 v[82:97], v[74:77], v[102:105], v[82:97]
	s_waitcnt lgkmcnt(8)
	v_mfma_f32_32x32x16_bf16 v[82:97], v[78:81], v[98:101], v[82:97]
	s_waitcnt lgkmcnt(7)
	v_mfma_f32_32x32x16_bf16 v[66:81], v[146:149], v[142:145], 0
	s_waitcnt lgkmcnt(6)
	v_mfma_f32_32x32x16_bf16 v[66:81], v[150:153], v[138:141], v[66:81]
	s_waitcnt lgkmcnt(5)
	v_mfma_f32_32x32x16_bf16 v[66:81], v[154:157], v[134:137], v[66:81]
	ds_read_b128 v[134:137], v0 offset:13056
	ds_read_b128 v[138:141], v0 offset:13088
	ds_read_b128 v[142:145], v0 offset:13120
	ds_read_b128 v[146:149], v0 offset:13152
	s_waitcnt lgkmcnt(8)
	v_mfma_f32_32x32x16_bf16 v[66:81], v[158:161], v[130:133], v[66:81]
	s_waitcnt lgkmcnt(7)
	v_mfma_f32_32x32x16_bf16 v[66:81], v[162:165], v[126:129], v[66:81]
	s_waitcnt lgkmcnt(6)
	v_mfma_f32_32x32x16_bf16 v[66:81], v[166:169], v[122:125], v[66:81]
	s_waitcnt lgkmcnt(5)
	v_mfma_f32_32x32x16_bf16 v[66:81], v[170:173], v[118:121], v[66:81]
	s_waitcnt lgkmcnt(4)
	v_mfma_f32_32x32x16_bf16 v[66:81], v[174:177], v[114:117], v[66:81]
	s_waitcnt lgkmcnt(3)
	v_mfma_f32_32x32x16_bf16 v[66:81], v[134:137], v[110:113], v[66:81]
	v_add_u32_e32 v0, s16, v205
	s_waitcnt lgkmcnt(2)
	v_mfma_f32_32x32x16_bf16 v[66:81], v[138:141], v[106:109], v[66:81]
	s_waitcnt lgkmcnt(1)
	v_mfma_f32_32x32x16_bf16 v[66:81], v[142:145], v[102:105], v[66:81]
	ds_read_b128 v[114:117], v0 offset:25600
	ds_read_b128 v[110:113], v0 offset:30208
	ds_read_b128 v[102:105], v0 offset:34816
	ds_read_b128 v[106:109], v0 offset:39424
	s_waitcnt lgkmcnt(4)
	v_mfma_f32_32x32x16_bf16 v[66:81], v[146:149], v[98:101], v[66:81]
	v_max_f32_e32 v98, v83, v83
	s_nop 10
	v_max_f32_e32 v99, v67, v67
	v_max_f32_e32 v98, v98, v99
	v_max_f32_e32 v99, v84, v84
	v_max_f32_e32 v100, v68, v68
	v_max_f32_e32 v99, v99, v100
	v_max_f32_e32 v100, v85, v85
	v_max_f32_e32 v101, v69, v69
	v_max3_f32 v98, v82, v66, v98
	v_max_f32_e32 v100, v100, v101
	v_max3_f32 v98, v98, v99, v100
	v_max_f32_e32 v99, v86, v86
	v_max_f32_e32 v100, v70, v70
	v_max_f32_e32 v99, v99, v100
	v_max_f32_e32 v100, v87, v87
	v_max_f32_e32 v101, v71, v71
	v_max_f32_e32 v100, v100, v101
	v_max3_f32 v98, v98, v99, v100
	v_max_f32_e32 v99, v88, v88
	v_max_f32_e32 v100, v72, v72
	v_max_f32_e32 v99, v99, v100
	v_max_f32_e32 v100, v89, v89
	v_max_f32_e32 v101, v73, v73
	v_max_f32_e32 v100, v100, v101
	v_max3_f32 v98, v98, v99, v100
	v_max_f32_e32 v99, v90, v90
	v_max_f32_e32 v100, v74, v74
	v_max_f32_e32 v99, v99, v100
	v_max_f32_e32 v100, v91, v91
	v_max_f32_e32 v101, v75, v75
	v_max_f32_e32 v100, v100, v101
	v_max3_f32 v98, v98, v99, v100
	v_max_f32_e32 v99, v92, v92
	v_max_f32_e32 v100, v76, v76
	v_max_f32_e32 v99, v99, v100
	v_max_f32_e32 v100, v93, v93
	v_max_f32_e32 v101, v77, v77
	v_max_f32_e32 v100, v100, v101
	v_max3_f32 v98, v98, v99, v100
	v_max_f32_e32 v99, v94, v94
	v_max_f32_e32 v100, v78, v78
	v_max_f32_e32 v99, v99, v100
	v_max_f32_e32 v100, v95, v95
	v_max_f32_e32 v101, v79, v79
	v_max_f32_e32 v100, v100, v101
	v_max3_f32 v98, v98, v99, v100
	v_max_f32_e32 v99, v96, v96
	v_max_f32_e32 v100, v80, v80
	v_max_f32_e32 v99, v99, v100
	v_max_f32_e32 v100, v97, v97
	v_max_f32_e32 v101, v81, v81
	v_max_f32_e32 v100, v100, v101
	v_max3_f32 v98, v98, v99, v100
	v_add_f32_e32 v99, 0x42800000, v214
	v_cmp_gt_f32_e32 vcc, v98, v99
	s_cbranch_vccz .LBB0_999
	v_mov_b32_e32 v99, v98
	s_nop 1
	v_permlane32_swap_b32_e32 v98, v99
	v_max3_f32 v98, v214, v98, v99
	v_sub_f32_e32 v99, v214, v98
	v_exp_f32_e32 v99, v99
	s_and_saveexec_b64 s[14:15], s[6:7]
	ds_write_b32 v191, v99
	s_or_b64 exec, exec, s[14:15]
	v_mul_f32_e32 v192, v192, v99
	s_waitcnt lgkmcnt(0)
	v_add_u32_e32 v99, v183, v182
	ds_read_b128 v[118:121], v99
	ds_read_b128 v[122:125], v99 offset:32
	ds_read_b128 v[126:129], v99 offset:64
	ds_read_b128 v[130:133], v99 offset:96
	s_waitcnt lgkmcnt(0)
	s_waitcnt lgkmcnt(3)
	v_pk_mul_f32 v[52:53], v[52:53], v[120:121]
	s_waitcnt lgkmcnt(2)
	v_pk_mul_f32 v[54:55], v[54:55], v[122:123]
	s_waitcnt lgkmcnt(1)
	v_pk_mul_f32 v[58:59], v[58:59], v[126:127]
	s_waitcnt lgkmcnt(0)
	v_pk_mul_f32 v[62:63], v[62:63], v[130:131]
	v_pk_mul_f32 v[64:65], v[64:65], v[132:133]
	v_pk_mul_f32 v[60:61], v[60:61], v[128:129]
	v_pk_mul_f32 v[56:57], v[56:57], v[124:125]
	v_pk_mul_f32 v[50:51], v[50:51], v[118:119]
	v_pk_mul_f32 v[46:47], v[46:47], v[130:131]
	v_pk_mul_f32 v[42:43], v[42:43], v[126:127]
	v_pk_mul_f32 v[38:39], v[38:39], v[122:123]
	v_pk_mul_f32 v[48:49], v[48:49], v[132:133]
	v_pk_mul_f32 v[44:45], v[44:45], v[128:129]
	v_pk_mul_f32 v[40:41], v[40:41], v[124:125]
	v_pk_mul_f32 v[36:37], v[36:37], v[120:121]
	v_pk_mul_f32 v[34:35], v[34:35], v[118:119]
	v_pk_mul_f32 v[30:31], v[30:31], v[130:131]
	v_pk_mul_f32 v[26:27], v[26:27], v[126:127]
	v_pk_mul_f32 v[22:23], v[22:23], v[122:123]
	v_pk_mul_f32 v[32:33], v[32:33], v[132:133]
	v_pk_mul_f32 v[28:29], v[28:29], v[128:129]
	v_pk_mul_f32 v[24:25], v[24:25], v[124:125]
	v_pk_mul_f32 v[20:21], v[20:21], v[120:121]
	v_pk_mul_f32 v[18:19], v[18:19], v[118:119]
	v_pk_mul_f32 v[14:15], v[14:15], v[130:131]
	v_pk_mul_f32 v[10:11], v[10:11], v[126:127]
	v_pk_mul_f32 v[6:7], v[6:7], v[122:123]
	v_pk_mul_f32 v[16:17], v[16:17], v[132:133]
	v_pk_mul_f32 v[12:13], v[12:13], v[128:129]
	v_pk_mul_f32 v[8:9], v[8:9], v[124:125]
	v_pk_mul_f32 v[4:5], v[4:5], v[120:121]
	v_pk_mul_f32 v[2:3], v[2:3], v[118:119]
	s_branch .LBB0_1000
